# phase 5: two rounds before the grid barrier, the 8 third-round tiles run after it while the other blocks start phase 6 (rounds rotated so dependent tiles come last, counter check before them)
# speedup vs baseline: 1.0091x; 1.0090x over previous
; #define PG8_LAS __attribute__((address_space(3)))
;   __device__ __forceinline__ void init(int nf, int ntiles) { NF = nf; tile_range(ntiles, lo, hi, step); }
; __device__ __forceinline__ void tile_range(int N, int& lo, int& hi, int& step) {
;   if ((gridDim.x & 7) == 0) {
;     const int x = blockIdx.x & 7, l = blockIdx.x >> 3;
;     lo = (int)((long long)x * N / 8) + l; hi = (int)((long long)(x + 1) * N / 8); step = gridDim.x >> 3;
;   } else { lo = blockIdx.x; hi = N; step = gridDim.x; }
; }
; __device__ void phase5(const Params& p, unsigned char* smem) {
;   TileSched S; S.init(4, 4 * 130);
;   pg8::Gemm g; g.A = (const u16*)(p.ws + OFF_M); g.Bt = (const u16*)(p.ws + OFF_WOUT); g.K = 1024;
;   EpiX1 E{p};
;   pg8::gemm_phase((PG8_LAS unsigned char*)smem, g, S, E);
; }
.LBB0_730:
	s_mov_b32 s101, 0
	s_cmp_gt_i32 s90, 5
	s_cselect_b64 s[0:1], -1, 0
	s_cmp_lt_i32 s91, 5
	s_cselect_b64 s[4:5], -1, 0
	s_or_b64 s[0:1], s[0:1], s[4:5]
	s_and_b64 vcc, exec, s[0:1]
	s_cbranch_vccnz .LBB0_782
.Lp5_reentry:
	s_load_dword s0, s[92:93], 0xc0
	s_add_u32 s6, s92, 0xc0
	s_addc_u32 s7, s93, 0
	s_waitcnt lgkmcnt(0)
	s_and_b32 s1, s0, 7
	s_cmp_lg_u32 s1, 0
	s_cbranch_scc0 .LBB0_733
	s_movk_i32 s3, 0x208
	s_mov_b32 s1, s94
	s_branch .LBB0_734

; __device__ __forceinline__ void tile_range(int N, int& lo, int& hi, int& step) {
;   if ((gridDim.x & 7) == 0) {
;     const int x = blockIdx.x & 7, l = blockIdx.x >> 3;
;     lo = (int)((long long)x * N / 8) + l; hi = (int)((long long)(x + 1) * N / 8); step = gridDim.x >> 3;
;   } else { lo = blockIdx.x; hi = N; step = gridDim.x; }
; }
.LBB0_734:
	s_cmp_eq_u32 s0, 32
	s_cbranch_scc0 .Lp5l_keep
	s_cmp_lt_i32 s91, 6
	s_cbranch_scc1 .Lp5l_keep
	s_cmp_eq_u32 s101, 0x5a17
	s_cbranch_scc1 .Lp5l_second
	s_add_i32 s3, s3, -1
	s_branch .Lp5l_keep
.Lp5l_second:
	s_add_i32 s1, s3, -1

; #define PG8_LAS __attribute__((address_space(3)))
;   __device__ __forceinline__ void init(int nf, int ntiles) { NF = nf; tile_range(ntiles, lo, hi, step); }
; __device__ void phase5(const Params& p, unsigned char* smem) {
;   TileSched S; S.init(4, 4 * 130);
;   pg8::Gemm g; g.A = (const u16*)(p.ws + OFF_M); g.Bt = (const u16*)(p.ws + OFF_WOUT); g.K = 1024;
;   EpiX1 E{p};
;   pg8::gemm_phase((PG8_LAS unsigned char*)smem, g, S, E);
; }
.LBB0_770:
	s_cmp_eq_u32 s101, 0x5a17
	s_cbranch_scc0 .Lp5l_first_end
	s_mov_b32 s101, 0
	v_cmp_eq_u32_e32 vcc, 0, v0
	s_and_saveexec_b64 s[4:5], vcc
	s_cbranch_execz .Lp5l_pub
	buffer_wbl2 sc1
	s_waitcnt vmcnt(0)
	v_mov_b32_e32 v2, 0xb23c00
	v_mov_b32_e32 v3, 1
	global_atomic_add v2, v3, s[88:89]
.Lp5l_pub:
	s_or_b64 exec, exec, s[4:5]
	s_branch .Lp6_entry

; #define RUN_PHASE(k, fn)                                  \
;   if (ph_lo <= k && k <= ph_hi) {                         \
;     if (k == PROBE_DUP) { fn(p, smem); cg::this_grid().sync(); } \
;     fn(p, smem);                                          \
;     if (k < ph_hi) cg::this_grid().sync();                \
;   }
; __global__ void __launch_bounds__(512) mega(Params p, int ph_lo, int ph_hi) {
;     ...
;   RUN_PHASE(5, phase5)
.Lgb4_done:
	s_or_b64 exec, exec, s[4:5]
	s_barrier
	s_lshr_b32 s8, s94, 3
	s_cmp_lg_u32 s8, 0
	s_cbranch_scc1 .LBB0_782
	s_load_dword s8, s[92:93], 0xc0
	s_waitcnt lgkmcnt(0)
	s_cmpk_eq_u32 s8, 0x100
	s_cbranch_scc0 .LBB0_782
	s_mov_b32 s101, 0x5a17
	s_branch .Lp5_reentry

; #define PG8_LAS __attribute__((address_space(3)))
;   __device__ __forceinline__ void init(int nf, int ntiles) { NF = nf; tile_range(ntiles, lo, hi, step); }
; __device__ __forceinline__ void tile_range(int N, int& lo, int& hi, int& step) {
;   if ((gridDim.x & 7) == 0) {
;     const int x = blockIdx.x & 7, l = blockIdx.x >> 3;
;     lo = (int)((long long)x * N / 8) + l; hi = (int)((long long)(x + 1) * N / 8); step = gridDim.x >> 3;
;   } else { lo = blockIdx.x; hi = N; step = gridDim.x; }
; }
; __device__ void phase6(const Params& p, unsigned char* smem) {
;   TileSched S; S.init(16, 16 * 130);
;   pg8::Gemm g; g.A = (const u16*)(p.ws + OFF_X1B); g.Bt = (const u16*)(p.ws + OFF_WUP); g.K = 1024;
;   EpiH E; E.ws = p.ws;
;   pg8::gemm_phase((PG8_LAS unsigned char*)smem, g, S, E);
.Lp6_entry:
	s_load_dword s0, s[92:93], 0xc0
	s_add_u32 s6, s92, 0xc0
	s_addc_u32 s7, s93, 0
	s_waitcnt lgkmcnt(0)
	s_and_b32 s1, s0, 7
	s_cmp_lg_u32 s1, 0
	s_cbranch_scc0 .LBB0_785
	s_movk_i32 s3, 0x820
	s_mov_b32 s1, s94
	s_branch .LBB0_786
.LBB0_785:
	s_and_b32 s3, s94, 7
	s_mul_i32 s4, s3, 0x104
	s_mulk_i32 s3, 0x820
	s_lshr_b32 s1, s94, 3
	s_addk_i32 s3, 0x820
	s_add_i32 s1, s4, s1
	s_lshr_b32 s3, s3, 3
	s_lshr_b32 s0, s0, 3
	s_sub_i32 s1, s1, s4
	s_sub_i32 s1, s0, s1
	s_add_i32 s1, s1, -1
	s_add_i32 s1, s1, s4
.LBB0_786:
	s_sub_i32 s62, s3, s1
	s_max_i32 s62, s62, 0
	s_add_i32 s62, s62, 31
	s_lshr_b32 s62, s62, 5
	s_mov_b32 s63, 0
	s_cmp_eq_u32 s0, 32
	s_cbranch_scc0 .Lp6r_norot
	s_cmp_lt_u32 s62, 3
	s_cbranch_scc1 .Lp6r_norot
	s_lshl_b32 s63, s62, 5
	s_add_i32 s1, s1, 64
	s_branch .Lp6r_set
.Lp6r_norot:
	s_mov_b32 s62, 0x7fffffff

; template <class Epi, class Sched>
; __device__ __forceinline__ void gemm_phase(PG8_LAS unsigned char* lds, const Gemm g, const Sched& S, const Epi& E) {
;     ...
;     for (;;) {
;         const bool has_next = S.next(ui + 1, nxt);
;         const char* nA = has_next ? (const char*)g.A + (size_t)nxt.pm * tstep : cA; const char* nB = has_next ? (const char*)g.Bt + (size_t)nxt.pn * tstep : cB;
;   __device__ __forceinline__ bool next(int i, pg8::Unit& u) const {
;     const int t = lo + i * step;
;     if (t >= hi) return false;
;     int ft, tt; tile_decode(t, NF, ft, tt); u.pm = tt; u.pn = ft; return true;
;   }
.LBB0_794:
	s_add_i32 s50, s50, 1
	s_cmp_eq_u32 s50, 5
	s_cbranch_scc0 .Lp6w_go
	s_cmp_eq_u32 s63, 0
	s_cbranch_scc1 .Lp6w_go
	s_mov_b64 exec, 1
	v_mov_b32_e32 v2, 0xb23c00
	v_mov_b32_e32 v3, 0
	s_movk_i32 s65, 0x2000
.Lp6w_spin:
	global_atomic_add v4, v2, v3, s[88:89] sc0
	s_waitcnt vmcnt(0)
	v_readfirstlane_b32 s66, v4
	s_cmp_ge_u32 s66, 8
	s_cbranch_scc1 .Lp6w_acq
	s_sleep 2
	s_sub_i32 s65, s65, 1
	s_cmp_lg_u32 s65, 0
	s_cbranch_scc1 .Lp6w_spin

;   __device__ __forceinline__ bool next(int i, pg8::Unit& u) const {
;     const int t = lo + i * step;
;     if (t >= hi) return false;
;     int ft, tt; tile_decode(t, NF, ft, tt); u.pm = tt; u.pn = ft; return true;
;   }
.Lp6w_go:
	s_mul_i32 s15, s50, s0
	s_add_i32 s15, s15, s1
	s_add_i32 s64, s50, 2
	s_cmp_ge_u32 s64, s62
	s_cselect_b32 s64, s63, 0
	s_sub_i32 s15, s15, s64
	s_cmp_ge_u32 s50, s62
	s_cselect_b32 s15, s3, s15
	s_cmp_lt_i32 s15, s3
	s_cselect_b64 s[30:31], -1, 0
	s_cmp_ge_i32 s15, s3
	s_cselect_b64 s[4:5], -1, 0
	s_and_b64 vcc, exec, s[4:5]
	s_cbranch_vccnz .LBB0_799
	s_cmpk_gt_i32 s15, 0x7ff
	s_mov_b64 s[18:19], -1
	s_cbranch_scc0 .LBB0_797
	s_add_i32 s14, s15, 0xfffff800
	s_and_b32 s16, s15, 1
	s_lshr_b32 s14, s14, 1
	s_bitset1_b32 s16, 7
	s_mov_b64 s[18:19], 0

; __global__ void __launch_bounds__(512) mega(Params p, int ph_lo, int ph_hi) {
;   __shared__ __align__(16) unsigned char smem[SMEM_BYTES];
	.amdhsa_kernel _Z4mega6Paramsii
		.amdhsa_group_segment_fixed_size 139264
		.amdhsa_private_segment_fixed_size 0
		.amdhsa_kernarg_size 448
		.amdhsa_user_sgpr_count 2
		.amdhsa_user_sgpr_dispatch_ptr 0
		.amdhsa_user_sgpr_queue_ptr 0
		.amdhsa_user_sgpr_kernarg_segment_ptr 1
		.amdhsa_user_sgpr_dispatch_id 0
		.amdhsa_user_sgpr_kernarg_preload_length 0
		.amdhsa_user_sgpr_kernarg_preload_offset 0
		.amdhsa_user_sgpr_private_segment_size 0
		.amdhsa_uses_dynamic_stack 0
		.amdhsa_enable_private_segment 0
		.amdhsa_system_sgpr_workgroup_id_x 1
		.amdhsa_system_sgpr_workgroup_id_y 0
		.amdhsa_system_sgpr_workgroup_id_z 0
		.amdhsa_system_sgpr_workgroup_info 0
		.amdhsa_system_vgpr_workitem_id 2
		.amdhsa_next_free_vgpr 240
		.amdhsa_next_free_sgpr 102
		.amdhsa_accum_offset 240
		.amdhsa_reserve_vcc 1
		.amdhsa_float_round_mode_32 0
		.amdhsa_float_round_mode_16_64 0
		.amdhsa_float_denorm_mode_32 3
		.amdhsa_float_denorm_mode_16_64 3
		.amdhsa_dx10_clamp 1
		.amdhsa_ieee_mode 1
		.amdhsa_fp16_overflow 0
		.amdhsa_tg_split 0
		.amdhsa_exception_fp_ieee_invalid_op 0
		.amdhsa_exception_fp_denorm_src 0
		.amdhsa_exception_fp_ieee_div_zero 0
		.amdhsa_exception_fp_ieee_overflow 0
		.amdhsa_exception_fp_ieee_underflow 0
		.amdhsa_exception_fp_ieee_inexact 0
		.amdhsa_exception_int_div_zero 0
	.end_amdhsa_kernel

; __global__ void __launch_bounds__(512) mega(Params p, int ph_lo, int ph_hi) {
;   __shared__ __align__(16) unsigned char smem[SMEM_BYTES];
amdhsa.kernels:
  - .agpr_count:     0
    .args:
      - .offset:         0
        .size:           184
        .value_kind:     by_value
      - .offset:         184
        .size:           4
        .value_kind:     by_value
      - .offset:         188
        .size:           4
        .value_kind:     by_value
      - .offset:         192
        .size:           4
        .value_kind:     hidden_block_count_x
      - .offset:         196
        .size:           4
        .value_kind:     hidden_block_count_y
      - .offset:         200
        .size:           4
        .value_kind:     hidden_block_count_z
      - .offset:         204
        .size:           2
        .value_kind:     hidden_group_size_x
      - .offset:         206
        .size:           2
        .value_kind:     hidden_group_size_y
      - .offset:         208
        .size:           2
        .value_kind:     hidden_group_size_z
      - .offset:         210
        .size:           2
        .value_kind:     hidden_remainder_x
      - .offset:         212
        .size:           2
        .value_kind:     hidden_remainder_y
      - .offset:         214
        .size:           2
        .value_kind:     hidden_remainder_z
      - .offset:         232
        .size:           8
        .value_kind:     hidden_global_offset_x
      - .offset:         240
        .size:           8
        .value_kind:     hidden_global_offset_y
      - .offset:         248
        .size:           8
        .value_kind:     hidden_global_offset_z
      - .offset:         256
        .size:           2
        .value_kind:     hidden_grid_dims
      - .offset:         280
        .size:           8
        .value_kind:     hidden_multigrid_sync_arg
    .group_segment_fixed_size: 139264
    .kernarg_segment_align: 8
    .kernarg_segment_size: 448
    .language:       OpenCL C
    .language_version:
      - 2
      - 0
    .max_flat_workgroup_size: 512
    .name:           _Z4mega6Paramsii
    .private_segment_fixed_size: 0
    .sgpr_count:     108
    .sgpr_spill_count: 92
    .symbol:         _Z4mega6Paramsii.kd
    .uniform_work_group_size: 1
    .uses_dynamic_stack: false
    .vgpr_count:     240
    .vgpr_spill_count: 0
    .wavefront_size: 64
